# attention: role B (waves 4-7) softmax of tile kt deferred to the start of the next interval (before PV of kt), with static priority for waves 0-3 (on v53)
# speedup vs baseline: 1.0069x; 1.0069x over previous
; __device__ __forceinline__ void att_qk_sm(const LAS unsigned char* kb, int klane, const bf16x8 (&qf)[12], f32x16 (&o)[4], float& mrun, float& lrun, bf16x8 (&pb)[4]) {
;     ...
;     float mx = fmaxf(s0[0], s1[0]);
; #pragma unroll
;     for (int i = 1; i < 16; ++i) asm("v_max3_f32 %0, %1, %2, %3" : "=v"(mx) : "v"(mx), "v"(s0[i]), "v"(s1[i]));
;     { const auto rr = __builtin_amdgcn_permlane32_swap(__float_as_uint(mx), __float_as_uint(mx), false, false);
;       mx = fmaxf(__uint_as_float(rr[0]), __uint_as_float(rr[1])); }
;     if (!__all(mx - mrun <= 8.0f)) {
;         const float mn = fmaxf(mrun, mx), al = __builtin_amdgcn_exp2f(mrun - mn);
;         mrun = mn; lrun *= al;
; #pragma unroll
;         for (int d = 0; d < 4; ++d) o[d] = o[d] * al;
;     }
; __device__ __forceinline__ void att_mfma(const Params& P, LAS unsigned char* lds, int wave) {
;     ...
;             if (!roleA && kt >= 1 && kt - 1 <= my_last) att_pv(lds + bprev * BUF, vlane, pb, o);
.LBB0_1016:
	s_cmp_lg_u32 s16, 0
	s_cselect_b64 s[4:5], -1, 0
	s_and_b64 s[4:5], s[0:1], s[4:5]
	s_cmp_le_u32 s16, s51
	s_cselect_b64 s[62:63], -1, 0
	s_and_b64 s[4:5], s[4:5], s[62:63]
	s_andn2_b64 vcc, exec, s[4:5]
	s_cbranch_vccnz .LBB0_1018
	v_max_f32_e32 v170, v64, v80
	v_max3_f32 v170, v170, v81, v65
	v_max3_f32 v170, v170, v82, v66
	v_max3_f32 v170, v170, v83, v67
	v_max3_f32 v170, v170, v84, v68
	v_max3_f32 v170, v170, v85, v69
	v_max3_f32 v170, v170, v86, v70
	v_max3_f32 v170, v170, v87, v71
	v_max3_f32 v170, v170, v88, v72
	v_max3_f32 v170, v170, v89, v73
	v_max3_f32 v170, v170, v90, v74
	v_max3_f32 v170, v170, v91, v75
	v_max3_f32 v170, v170, v92, v76
	v_max3_f32 v170, v170, v93, v77
	v_max3_f32 v170, v170, v94, v78
	v_max3_f32 v170, v170, v95, v79
	v_mov_b32_e32 v171, v170
	s_nop 1
	v_permlane32_swap_b32_e32 v170, v171
	v_max_f32_e32 v170, v170, v171
	v_sub_f32_e32 v171, v170, v169
	v_cmp_ge_f32_e32 vcc, s37, v171
	s_cmp_eq_u64 vcc, exec
	s_cbranch_scc1 .Latt_smh_noresc
	v_max_f32_e32 v170, v170, v170
	v_max_f32_e32 v171, v169, v169
	v_max_f32_e32 v171, v171, v170
	v_sub_f32_e32 v169, v169, v171
	v_exp_f32_e32 v170, v169
	v_mov_b32_e32 v169, v171
	v_mul_f32_e32 v168, v168, v170
	v_pk_mul_f32 v[62:63], v[62:63], v[170:171] op_sel_hi:[1,0]
	v_pk_mul_f32 v[60:61], v[60:61], v[170:171] op_sel_hi:[1,0]
	v_pk_mul_f32 v[58:59], v[58:59], v[170:171] op_sel_hi:[1,0]
	v_pk_mul_f32 v[56:57], v[56:57], v[170:171] op_sel_hi:[1,0]
	v_pk_mul_f32 v[54:55], v[54:55], v[170:171] op_sel_hi:[1,0]
	v_pk_mul_f32 v[52:53], v[52:53], v[170:171] op_sel_hi:[1,0]
	v_pk_mul_f32 v[50:51], v[50:51], v[170:171] op_sel_hi:[1,0]
	v_pk_mul_f32 v[48:49], v[48:49], v[170:171] op_sel_hi:[1,0]
	v_pk_mul_f32 v[46:47], v[46:47], v[170:171] op_sel_hi:[1,0]
	v_pk_mul_f32 v[44:45], v[44:45], v[170:171] op_sel_hi:[1,0]
	v_pk_mul_f32 v[42:43], v[42:43], v[170:171] op_sel_hi:[1,0]
	v_pk_mul_f32 v[40:41], v[40:41], v[170:171] op_sel_hi:[1,0]
	v_pk_mul_f32 v[38:39], v[38:39], v[170:171] op_sel_hi:[1,0]
	v_pk_mul_f32 v[36:37], v[36:37], v[170:171] op_sel_hi:[1,0]
	v_pk_mul_f32 v[34:35], v[34:35], v[170:171] op_sel_hi:[1,0]
	v_pk_mul_f32 v[32:33], v[32:33], v[170:171] op_sel_hi:[1,0]
	v_pk_mul_f32 v[30:31], v[30:31], v[170:171] op_sel_hi:[1,0]
	v_pk_mul_f32 v[28:29], v[28:29], v[170:171] op_sel_hi:[1,0]
	v_pk_mul_f32 v[26:27], v[26:27], v[170:171] op_sel_hi:[1,0]
	v_pk_mul_f32 v[24:25], v[24:25], v[170:171] op_sel_hi:[1,0]
	v_pk_mul_f32 v[22:23], v[22:23], v[170:171] op_sel_hi:[1,0]
	v_pk_mul_f32 v[20:21], v[20:21], v[170:171] op_sel_hi:[1,0]
	v_pk_mul_f32 v[18:19], v[18:19], v[170:171] op_sel_hi:[1,0]
	v_pk_mul_f32 v[16:17], v[16:17], v[170:171] op_sel_hi:[1,0]
	v_pk_mul_f32 v[14:15], v[14:15], v[170:171] op_sel_hi:[1,0]
	v_pk_mul_f32 v[12:13], v[12:13], v[170:171] op_sel_hi:[1,0]
	v_pk_mul_f32 v[10:11], v[10:11], v[170:171] op_sel_hi:[1,0]
	v_pk_mul_f32 v[8:9], v[8:9], v[170:171] op_sel_hi:[1,0]
	v_pk_mul_f32 v[6:7], v[6:7], v[170:171] op_sel_hi:[1,0]
	v_pk_mul_f32 v[4:5], v[4:5], v[170:171] op_sel_hi:[1,0]
	v_pk_mul_f32 v[2:3], v[2:3], v[170:171] op_sel_hi:[1,0]
	v_pk_mul_f32 v[0:1], v[0:1], v[170:171] op_sel_hi:[1,0]
; #define LAS __attribute__((address_space(3)))
; #define TR_READ(dst, addr, off) asm volatile("ds_read_b64_tr_b16 %0, %1 offset:%c2" : "=v"(dst) : "v"(addr), "i"(off) : "memory")
; __device__ __forceinline__ void att_qk_sm(const LAS unsigned char* kb, int klane, const bf16x8 (&qf)[12], f32x16 (&o)[4], float& mrun, float& lrun, bf16x8 (&pb)[4]) {
;     ...
;     float ps = 0.f;
; #pragma unroll
;     for (int i = 0; i < 16; ++i) { s0[i] = __builtin_amdgcn_exp2f(s0[i] - mrun); s1[i] = __builtin_amdgcn_exp2f(s1[i] - mrun); ps += s0[i] + s1[i]; }
;     lrun += ps;
;     pb[0] = pack8bf(s0[0], s0[1], s0[2], s0[3], s0[4], s0[5], s0[6], s0[7]);
;     pb[1] = pack8bf(s0[8], s0[9], s0[10], s0[11], s0[12], s0[13], s0[14], s0[15]);
;     pb[2] = pack8bf(s1[0], s1[1], s1[2], s1[3], s1[4], s1[5], s1[6], s1[7]);
;     pb[3] = pack8bf(s1[8], s1[9], s1[10], s1[11], s1[12], s1[13], s1[14], s1[15]);
;     __builtin_amdgcn_sched_barrier(0);
; __device__ __forceinline__ void att_pv(const LAS unsigned char* kb, int vlane, const bf16x8 (&pb)[4], f32x16 (&o)[4]) {
;     constexpr int VP = 320;
;     s16x4 vlo[2][4], vhi[2][4];
;     const unsigned vaddr = (unsigned)(unsigned long)(kb + vlane);
; #pragma unroll
;     for (int d = 0; d < 4; ++d) { TR_READ(vlo[0][d], vaddr, d * 64); TR_READ(vhi[0][d], vaddr, 8 * VP + d * 64); }
; #pragma unroll
;     for (int ks = 0; ks < 4; ++ks) {
;         if (ks < 3) {
; #pragma unroll
;             for (int d = 0; d < 4; ++d) { TR_READ(vlo[(ks + 1) & 1][d], vaddr, ((ks + 1) * 16) * VP + d * 64); TR_READ(vhi[(ks + 1) & 1][d], vaddr, ((ks + 1) * 16 + 8) * VP + d * 64); }
;             TR_WAIT4(8, vlo[ks & 1][0], vlo[ks & 1][1], vlo[ks & 1][2], vlo[ks & 1][3]); TR_WAIT4(8, vhi[ks & 1][0], vhi[ks & 1][1], vhi[ks & 1][2], vhi[ks & 1][3]);
;         } else {
;             TR_WAIT4(0, vlo[ks & 1][0], vlo[ks & 1][1], vlo[ks & 1][2], vlo[ks & 1][3]); TR_WAIT4(0, vhi[ks & 1][0], vhi[ks & 1][1], vhi[ks & 1][2], vhi[ks & 1][3]);
;         }
;         __builtin_amdgcn_sched_barrier(0);
; #pragma unroll
;         for (int d = 0; d < 4; ++d) { const bf16x8 a = __builtin_shufflevector(vlo[ks & 1][d], vhi[ks & 1][d], 0, 1, 2, 3, 4, 5, 6, 7);
;             o[d] = __builtin_amdgcn_mfma_f32_32x32x16_bf16(a, pb[ks], o[d], 0, 0, 0); }
;         __builtin_amdgcn_sched_barrier(0);
;     }
; }
.Latt_smh_noresc:
	v_mov_b32_e32 v170, v169
	v_sub_f32_e32 v80, v80, v169
	v_sub_f32_e32 v81, v81, v169
	v_sub_f32_e32 v82, v82, v169
	v_sub_f32_e32 v83, v83, v169
	v_sub_f32_e32 v84, v84, v169
	v_sub_f32_e32 v85, v85, v169
	v_sub_f32_e32 v86, v86, v169
	v_sub_f32_e32 v87, v87, v169
	v_sub_f32_e32 v88, v88, v169
	v_sub_f32_e32 v89, v89, v169
	v_sub_f32_e32 v90, v90, v169
	v_sub_f32_e32 v91, v91, v169
	v_sub_f32_e32 v92, v92, v169
	v_sub_f32_e32 v93, v93, v169
	v_sub_f32_e32 v94, v94, v169
	v_sub_f32_e32 v95, v95, v169
	v_sub_f32_e32 v64, v64, v169
	v_sub_f32_e32 v65, v65, v169
	v_sub_f32_e32 v66, v66, v169
	v_sub_f32_e32 v67, v67, v169
	v_sub_f32_e32 v68, v68, v169
	v_sub_f32_e32 v69, v69, v169
	v_sub_f32_e32 v70, v70, v169
	v_sub_f32_e32 v71, v71, v169
	v_sub_f32_e32 v72, v72, v169
	v_sub_f32_e32 v73, v73, v169
	v_sub_f32_e32 v74, v74, v169
	v_sub_f32_e32 v75, v75, v169
	v_sub_f32_e32 v76, v76, v169
	v_sub_f32_e32 v77, v77, v169
	v_sub_f32_e32 v78, v78, v169
	v_sub_f32_e32 v79, v79, v169
	v_exp_f32_e32 v80, v80
	v_exp_f32_e32 v81, v81
	v_exp_f32_e32 v82, v82
	v_exp_f32_e32 v83, v83
	v_exp_f32_e32 v84, v84
	v_exp_f32_e32 v85, v85
	v_exp_f32_e32 v86, v86
	v_exp_f32_e32 v87, v87
	v_exp_f32_e32 v88, v88
	v_exp_f32_e32 v89, v89
	v_exp_f32_e32 v90, v90
	v_exp_f32_e32 v91, v91
	v_exp_f32_e32 v92, v92
	v_exp_f32_e32 v93, v93
	v_exp_f32_e32 v94, v94
	v_exp_f32_e32 v95, v95
	v_exp_f32_e32 v64, v64
	v_exp_f32_e32 v65, v65
	v_exp_f32_e32 v66, v66
	v_exp_f32_e32 v67, v67
	v_exp_f32_e32 v68, v68
	v_exp_f32_e32 v69, v69
	v_exp_f32_e32 v70, v70
	v_exp_f32_e32 v71, v71
	v_exp_f32_e32 v72, v72
	v_exp_f32_e32 v73, v73
	v_exp_f32_e32 v74, v74
	v_exp_f32_e32 v75, v75
	v_exp_f32_e32 v76, v76
	v_exp_f32_e32 v77, v77
	v_exp_f32_e32 v78, v78
	v_exp_f32_e32 v79, v79
	v_pk_add_f32 v[172:173], v[80:81], v[82:83]
	v_pk_add_f32 v[174:175], v[84:85], v[86:87]
	v_pk_add_f32 v[176:177], v[88:89], v[90:91]
	v_pk_add_f32 v[178:179], v[92:93], v[94:95]
	v_pk_add_f32 v[172:173], v[172:173], v[64:65]
	v_pk_add_f32 v[174:175], v[174:175], v[66:67]
	v_pk_add_f32 v[176:177], v[176:177], v[68:69]
	v_pk_add_f32 v[178:179], v[178:179], v[70:71]
	v_pk_add_f32 v[172:173], v[172:173], v[72:73]
	v_pk_add_f32 v[174:175], v[174:175], v[74:75]
	v_pk_add_f32 v[176:177], v[176:177], v[76:77]
	v_pk_add_f32 v[178:179], v[178:179], v[78:79]
	v_pk_add_f32 v[172:173], v[172:173], v[174:175]
	v_pk_add_f32 v[176:177], v[176:177], v[178:179]
	v_cvt_pk_bf16_f32 v71, v70, v71
	v_cvt_pk_bf16_f32 v70, v68, v69
	v_cvt_pk_bf16_f32 v69, v66, v67
	v_cvt_pk_bf16_f32 v68, v64, v65
	v_pk_add_f32 v[172:173], v[172:173], v[176:177]
	v_cvt_pk_bf16_f32 v64, v72, v73
	v_cvt_pk_bf16_f32 v65, v74, v75
	v_cvt_pk_bf16_f32 v66, v76, v77
	v_cvt_pk_bf16_f32 v67, v78, v79
	v_add_f32_e32 v170, v172, v173
	v_cvt_pk_bf16_f32 v72, v88, v89
	v_cvt_pk_bf16_f32 v73, v90, v91
	v_cvt_pk_bf16_f32 v74, v92, v93
	v_cvt_pk_bf16_f32 v75, v94, v95
	v_add_f32_e32 v168, v168, v170
	v_cvt_pk_bf16_f32 v76, v80, v81
	v_cvt_pk_bf16_f32 v77, v82, v83
	v_cvt_pk_bf16_f32 v78, v84, v85
	v_cvt_pk_bf16_f32 v79, v86, v87
	v_add_u32_e32 v80, s77, v222
	v_add_u32_e32 v186, 0x6400, v80
	ds_read_b64_tr_b16 v[80:81], v186 offset:0
	ds_read_b64_tr_b16 v[82:83], v186 offset:2560
	ds_read_b64_tr_b16 v[84:85], v186 offset:64
	ds_read_b64_tr_b16 v[86:87], v186 offset:2624
	ds_read_b64_tr_b16 v[88:89], v186 offset:128
	ds_read_b64_tr_b16 v[90:91], v186 offset:2688
	ds_read_b64_tr_b16 v[92:93], v186 offset:192
	ds_read_b64_tr_b16 v[94:95], v186 offset:2752
	ds_read_b64_tr_b16 v[170:171], v186 offset:5120
	ds_read_b64_tr_b16 v[172:173], v186 offset:7680
	ds_read_b64_tr_b16 v[174:175], v186 offset:5184
	ds_read_b64_tr_b16 v[176:177], v186 offset:7744
	ds_read_b64_tr_b16 v[178:179], v186 offset:5248
	ds_read_b64_tr_b16 v[180:181], v186 offset:7808
	ds_read_b64_tr_b16 v[182:183], v186 offset:5312
	ds_read_b64_tr_b16 v[184:185], v186 offset:7872
	s_waitcnt lgkmcnt(8)
	v_mfma_f32_32x32x16_bf16 v[48:63], v[80:83], v[76:79], v[48:63]
	v_mfma_f32_32x32x16_bf16 v[32:47], v[84:87], v[76:79], v[32:47]
	v_mfma_f32_32x32x16_bf16 v[16:31], v[88:91], v[76:79], v[16:31]
	v_mfma_f32_32x32x16_bf16 v[0:15], v[92:95], v[76:79], v[0:15]
	ds_read_b64_tr_b16 v[80:81], v186 offset:10240
	ds_read_b64_tr_b16 v[82:83], v186 offset:12800
	ds_read_b64_tr_b16 v[84:85], v186 offset:10304
	ds_read_b64_tr_b16 v[86:87], v186 offset:12864
	ds_read_b64_tr_b16 v[88:89], v186 offset:10368
	ds_read_b64_tr_b16 v[90:91], v186 offset:12928
	ds_read_b64_tr_b16 v[92:93], v186 offset:10432
	ds_read_b64_tr_b16 v[94:95], v186 offset:12992
	s_waitcnt lgkmcnt(8)
	v_mfma_f32_32x32x16_bf16 v[48:63], v[170:173], v[72:75], v[48:63]
	v_mfma_f32_32x32x16_bf16 v[32:47], v[174:177], v[72:75], v[32:47]
	v_mfma_f32_32x32x16_bf16 v[16:31], v[178:181], v[72:75], v[16:31]
	v_mfma_f32_32x32x16_bf16 v[0:15], v[182:185], v[72:75], v[0:15]
	ds_read_b64_tr_b16 v[170:171], v186 offset:15360
	ds_read_b64_tr_b16 v[172:173], v186 offset:17920
	ds_read_b64_tr_b16 v[174:175], v186 offset:15424
	ds_read_b64_tr_b16 v[176:177], v186 offset:17984
	ds_read_b64_tr_b16 v[178:179], v186 offset:15488
	ds_read_b64_tr_b16 v[180:181], v186 offset:18048
	ds_read_b64_tr_b16 v[182:183], v186 offset:15552
	ds_read_b64_tr_b16 v[184:185], v186 offset:18112
	s_waitcnt lgkmcnt(8)
	v_mfma_f32_32x32x16_bf16 v[48:63], v[80:83], v[68:71], v[48:63]
	v_mfma_f32_32x32x16_bf16 v[32:47], v[84:87], v[68:71], v[32:47]
	v_mfma_f32_32x32x16_bf16 v[16:31], v[88:91], v[68:71], v[16:31]
	v_mfma_f32_32x32x16_bf16 v[0:15], v[92:95], v[68:71], v[0:15]
	s_waitcnt lgkmcnt(0)
	v_mfma_f32_32x32x16_bf16 v[48:63], v[170:173], v[64:67], v[48:63]
	v_mfma_f32_32x32x16_bf16 v[32:47], v[174:177], v[64:67], v[32:47]
	v_mfma_f32_32x32x16_bf16 v[16:31], v[178:181], v[64:67], v[16:31]
	v_mfma_f32_32x32x16_bf16 v[0:15], v[182:185], v[64:67], v[0:15]

; __device__ __forceinline__ void att_qk_sm(const LAS unsigned char* kb, int klane, const bf16x8 (&qf)[12], f32x16 (&o)[4], float& mrun, float& lrun, bf16x8 (&pb)[4]) {
;     ...
;     float mx = fmaxf(s0[0], s1[0]);
; #pragma unroll
;     for (int i = 1; i < 16; ++i) asm("v_max3_f32 %0, %1, %2, %3" : "=v"(mx) : "v"(mx), "v"(s0[i]), "v"(s1[i]));
;     { const auto rr = __builtin_amdgcn_permlane32_swap(__float_as_uint(mx), __float_as_uint(mx), false, false);
;       mx = fmaxf(__uint_as_float(rr[0]), __uint_as_float(rr[1])); }
;     if (!__all(mx - mrun <= 8.0f)) {
;         const float mn = fmaxf(mrun, mx), al = __builtin_amdgcn_exp2f(mrun - mn);
;         mrun = mn; lrun *= al;
; #pragma unroll
;         for (int d = 0; d < 4; ++d) o[d] = o[d] * al;
;     }
.Latt_issued_q:
	s_and_b64 vcc, exec, s[0:1]
	s_cbranch_vccnz .LBB0_1022
	v_max_f32_e32 v170, v64, v80
	v_max3_f32 v170, v170, v81, v65
	v_max3_f32 v170, v170, v82, v66
	v_max3_f32 v170, v170, v83, v67
	v_max3_f32 v170, v170, v84, v68
	v_max3_f32 v170, v170, v85, v69
	v_max3_f32 v170, v170, v86, v70
	v_max3_f32 v170, v170, v87, v71
	v_max3_f32 v170, v170, v88, v72
	v_max3_f32 v170, v170, v89, v73
	v_max3_f32 v170, v170, v90, v74
	v_max3_f32 v170, v170, v91, v75
	v_max3_f32 v170, v170, v92, v76
	v_max3_f32 v170, v170, v93, v77
	v_max3_f32 v170, v170, v94, v78
	v_max3_f32 v170, v170, v95, v79
	v_mov_b32_e32 v171, v170
	s_nop 1
	v_permlane32_swap_b32_e32 v170, v171
	v_max_f32_e32 v170, v170, v171
	v_sub_f32_e32 v171, v170, v169
	v_cmp_ge_f32_e32 vcc, s37, v171
	s_cmp_eq_u64 vcc, exec
	s_cbranch_scc1 .LBB0_1021
	v_max_f32_e32 v170, v170, v170
	v_max_f32_e32 v171, v169, v169
	v_max_f32_e32 v171, v171, v170
	v_sub_f32_e32 v169, v169, v171
	v_exp_f32_e32 v170, v169
	v_mov_b32_e32 v169, v171
	v_mul_f32_e32 v168, v168, v170
	v_pk_mul_f32 v[62:63], v[62:63], v[170:171] op_sel_hi:[1,0]
	v_pk_mul_f32 v[60:61], v[60:61], v[170:171] op_sel_hi:[1,0]
	v_pk_mul_f32 v[58:59], v[58:59], v[170:171] op_sel_hi:[1,0]
	v_pk_mul_f32 v[56:57], v[56:57], v[170:171] op_sel_hi:[1,0]
	v_pk_mul_f32 v[54:55], v[54:55], v[170:171] op_sel_hi:[1,0]
	v_pk_mul_f32 v[52:53], v[52:53], v[170:171] op_sel_hi:[1,0]
	v_pk_mul_f32 v[50:51], v[50:51], v[170:171] op_sel_hi:[1,0]
	v_pk_mul_f32 v[48:49], v[48:49], v[170:171] op_sel_hi:[1,0]
	v_pk_mul_f32 v[46:47], v[46:47], v[170:171] op_sel_hi:[1,0]
	v_pk_mul_f32 v[44:45], v[44:45], v[170:171] op_sel_hi:[1,0]
	v_pk_mul_f32 v[42:43], v[42:43], v[170:171] op_sel_hi:[1,0]
	v_pk_mul_f32 v[40:41], v[40:41], v[170:171] op_sel_hi:[1,0]
	v_pk_mul_f32 v[38:39], v[38:39], v[170:171] op_sel_hi:[1,0]
	v_pk_mul_f32 v[36:37], v[36:37], v[170:171] op_sel_hi:[1,0]
	v_pk_mul_f32 v[34:35], v[34:35], v[170:171] op_sel_hi:[1,0]
	v_pk_mul_f32 v[32:33], v[32:33], v[170:171] op_sel_hi:[1,0]
	v_pk_mul_f32 v[30:31], v[30:31], v[170:171] op_sel_hi:[1,0]
	v_pk_mul_f32 v[28:29], v[28:29], v[170:171] op_sel_hi:[1,0]
	v_pk_mul_f32 v[26:27], v[26:27], v[170:171] op_sel_hi:[1,0]
	v_pk_mul_f32 v[24:25], v[24:25], v[170:171] op_sel_hi:[1,0]
	v_pk_mul_f32 v[22:23], v[22:23], v[170:171] op_sel_hi:[1,0]
	v_pk_mul_f32 v[20:21], v[20:21], v[170:171] op_sel_hi:[1,0]
	v_pk_mul_f32 v[18:19], v[18:19], v[170:171] op_sel_hi:[1,0]
	v_pk_mul_f32 v[16:17], v[16:17], v[170:171] op_sel_hi:[1,0]
	v_pk_mul_f32 v[14:15], v[14:15], v[170:171] op_sel_hi:[1,0]
	v_pk_mul_f32 v[12:13], v[12:13], v[170:171] op_sel_hi:[1,0]
	v_pk_mul_f32 v[10:11], v[10:11], v[170:171] op_sel_hi:[1,0]
	v_pk_mul_f32 v[8:9], v[8:9], v[170:171] op_sel_hi:[1,0]
	v_pk_mul_f32 v[6:7], v[6:7], v[170:171] op_sel_hi:[1,0]
	v_pk_mul_f32 v[4:5], v[4:5], v[170:171] op_sel_hi:[1,0]
	v_pk_mul_f32 v[2:3], v[2:3], v[170:171] op_sel_hi:[1,0]
	v_pk_mul_f32 v[0:1], v[0:1], v[170:171] op_sel_hi:[1,0]

; __device__ __forceinline__ void att_qk_sm(const LAS unsigned char* kb, int klane, const bf16x8 (&qf)[12], f32x16 (&o)[4], float& mrun, float& lrun, bf16x8 (&pb)[4]) {
;     ...
;     float mx = fmaxf(s0[0], s1[0]);
; #pragma unroll
;     for (int i = 1; i < 16; ++i) asm("v_max3_f32 %0, %1, %2, %3" : "=v"(mx) : "v"(mx), "v"(s0[i]), "v"(s1[i]));
;     { const auto rr = __builtin_amdgcn_permlane32_swap(__float_as_uint(mx), __float_as_uint(mx), false, false);
;       mx = fmaxf(__uint_as_float(rr[0]), __uint_as_float(rr[1])); }
;     if (!__all(mx - mrun <= 8.0f)) {
;         const float mn = fmaxf(mrun, mx), al = __builtin_amdgcn_exp2f(mrun - mn);
;         mrun = mn; lrun *= al;
; #pragma unroll
;         for (int d = 0; d < 4; ++d) o[d] = o[d] * al;
;     }
; __device__ __forceinline__ void att_mfma(const Params& P, LAS unsigned char* lds, int wave) {
;     ...
;         if (!roleA && ntile - 1 <= my_last) att_pv(lds + bprev * BUF, vlane, pb, o);
.LBB0_1026:
	s_and_b64 vcc, exec, s[8:9]
	s_cbranch_vccz .LBB0_1007
	v_max_f32_e32 v170, v64, v80
	v_max3_f32 v170, v170, v81, v65
	v_max3_f32 v170, v170, v82, v66
	v_max3_f32 v170, v170, v83, v67
	v_max3_f32 v170, v170, v84, v68
	v_max3_f32 v170, v170, v85, v69
	v_max3_f32 v170, v170, v86, v70
	v_max3_f32 v170, v170, v87, v71
	v_max3_f32 v170, v170, v88, v72
	v_max3_f32 v170, v170, v89, v73
	v_max3_f32 v170, v170, v90, v74
	v_max3_f32 v170, v170, v91, v75
	v_max3_f32 v170, v170, v92, v76
	v_max3_f32 v170, v170, v93, v77
	v_max3_f32 v170, v170, v94, v78
	v_max3_f32 v170, v170, v95, v79
	v_mov_b32_e32 v171, v170
	s_nop 1
	v_permlane32_swap_b32_e32 v170, v171
	v_max_f32_e32 v170, v170, v171
	v_sub_f32_e32 v171, v170, v169
	v_cmp_ge_f32_e32 vcc, s37, v171
	s_cmp_eq_u64 vcc, exec
	s_cbranch_scc1 .Latt_smt_noresc
	v_max_f32_e32 v170, v170, v170
	v_max_f32_e32 v171, v169, v169
	v_max_f32_e32 v171, v171, v170
	v_sub_f32_e32 v169, v169, v171
	v_exp_f32_e32 v170, v169
	v_mov_b32_e32 v169, v171
	v_mul_f32_e32 v168, v168, v170
	v_pk_mul_f32 v[62:63], v[62:63], v[170:171] op_sel_hi:[1,0]
	v_pk_mul_f32 v[60:61], v[60:61], v[170:171] op_sel_hi:[1,0]
	v_pk_mul_f32 v[58:59], v[58:59], v[170:171] op_sel_hi:[1,0]
	v_pk_mul_f32 v[56:57], v[56:57], v[170:171] op_sel_hi:[1,0]
	v_pk_mul_f32 v[54:55], v[54:55], v[170:171] op_sel_hi:[1,0]
	v_pk_mul_f32 v[52:53], v[52:53], v[170:171] op_sel_hi:[1,0]
	v_pk_mul_f32 v[50:51], v[50:51], v[170:171] op_sel_hi:[1,0]
	v_pk_mul_f32 v[48:49], v[48:49], v[170:171] op_sel_hi:[1,0]
	v_pk_mul_f32 v[46:47], v[46:47], v[170:171] op_sel_hi:[1,0]
	v_pk_mul_f32 v[44:45], v[44:45], v[170:171] op_sel_hi:[1,0]
	v_pk_mul_f32 v[42:43], v[42:43], v[170:171] op_sel_hi:[1,0]
	v_pk_mul_f32 v[40:41], v[40:41], v[170:171] op_sel_hi:[1,0]
	v_pk_mul_f32 v[38:39], v[38:39], v[170:171] op_sel_hi:[1,0]
	v_pk_mul_f32 v[36:37], v[36:37], v[170:171] op_sel_hi:[1,0]
	v_pk_mul_f32 v[34:35], v[34:35], v[170:171] op_sel_hi:[1,0]
	v_pk_mul_f32 v[32:33], v[32:33], v[170:171] op_sel_hi:[1,0]
	v_pk_mul_f32 v[30:31], v[30:31], v[170:171] op_sel_hi:[1,0]
	v_pk_mul_f32 v[28:29], v[28:29], v[170:171] op_sel_hi:[1,0]
	v_pk_mul_f32 v[26:27], v[26:27], v[170:171] op_sel_hi:[1,0]
	v_pk_mul_f32 v[24:25], v[24:25], v[170:171] op_sel_hi:[1,0]
	v_pk_mul_f32 v[22:23], v[22:23], v[170:171] op_sel_hi:[1,0]
	v_pk_mul_f32 v[20:21], v[20:21], v[170:171] op_sel_hi:[1,0]
	v_pk_mul_f32 v[18:19], v[18:19], v[170:171] op_sel_hi:[1,0]
	v_pk_mul_f32 v[16:17], v[16:17], v[170:171] op_sel_hi:[1,0]
	v_pk_mul_f32 v[14:15], v[14:15], v[170:171] op_sel_hi:[1,0]
	v_pk_mul_f32 v[12:13], v[12:13], v[170:171] op_sel_hi:[1,0]
	v_pk_mul_f32 v[10:11], v[10:11], v[170:171] op_sel_hi:[1,0]
	v_pk_mul_f32 v[8:9], v[8:9], v[170:171] op_sel_hi:[1,0]
	v_pk_mul_f32 v[6:7], v[6:7], v[170:171] op_sel_hi:[1,0]
	v_pk_mul_f32 v[4:5], v[4:5], v[170:171] op_sel_hi:[1,0]
	v_pk_mul_f32 v[2:3], v[2:3], v[170:171] op_sel_hi:[1,0]
	v_pk_mul_f32 v[0:1], v[0:1], v[170:171] op_sel_hi:[1,0]
; #define LAS __attribute__((address_space(3)))
; #define TR_READ(dst, addr, off) asm volatile("ds_read_b64_tr_b16 %0, %1 offset:%c2" : "=v"(dst) : "v"(addr), "i"(off) : "memory")
; __device__ __forceinline__ void att_qk_sm(const LAS unsigned char* kb, int klane, const bf16x8 (&qf)[12], f32x16 (&o)[4], float& mrun, float& lrun, bf16x8 (&pb)[4]) {
;     ...
;     float ps = 0.f;
; #pragma unroll
;     for (int i = 0; i < 16; ++i) { s0[i] = __builtin_amdgcn_exp2f(s0[i] - mrun); s1[i] = __builtin_amdgcn_exp2f(s1[i] - mrun); ps += s0[i] + s1[i]; }
;     lrun += ps;
;     pb[0] = pack8bf(s0[0], s0[1], s0[2], s0[3], s0[4], s0[5], s0[6], s0[7]);
;     pb[1] = pack8bf(s0[8], s0[9], s0[10], s0[11], s0[12], s0[13], s0[14], s0[15]);
;     pb[2] = pack8bf(s1[0], s1[1], s1[2], s1[3], s1[4], s1[5], s1[6], s1[7]);
;     pb[3] = pack8bf(s1[8], s1[9], s1[10], s1[11], s1[12], s1[13], s1[14], s1[15]);
;     __builtin_amdgcn_sched_barrier(0);
; }
; __device__ __forceinline__ void att_pv(const LAS unsigned char* kb, int vlane, const bf16x8 (&pb)[4], f32x16 (&o)[4]) {
;     constexpr int VP = 320;
;     s16x4 vlo[2][4], vhi[2][4];
;     const unsigned vaddr = (unsigned)(unsigned long)(kb + vlane);
; #pragma unroll
;     for (int d = 0; d < 4; ++d) { TR_READ(vlo[0][d], vaddr, d * 64); TR_READ(vhi[0][d], vaddr, 8 * VP + d * 64); }
; #pragma unroll
;     for (int ks = 0; ks < 4; ++ks) {
;         if (ks < 3) {
; #pragma unroll
;             for (int d = 0; d < 4; ++d) { TR_READ(vlo[(ks + 1) & 1][d], vaddr, ((ks + 1) * 16) * VP + d * 64); TR_READ(vhi[(ks + 1) & 1][d], vaddr, ((ks + 1) * 16 + 8) * VP + d * 64); }
;             TR_WAIT4(8, vlo[ks & 1][0], vlo[ks & 1][1], vlo[ks & 1][2], vlo[ks & 1][3]); TR_WAIT4(8, vhi[ks & 1][0], vhi[ks & 1][1], vhi[ks & 1][2], vhi[ks & 1][3]);
;         } else {
;             TR_WAIT4(0, vlo[ks & 1][0], vlo[ks & 1][1], vlo[ks & 1][2], vlo[ks & 1][3]); TR_WAIT4(0, vhi[ks & 1][0], vhi[ks & 1][1], vhi[ks & 1][2], vhi[ks & 1][3]);
;         }
;         __builtin_amdgcn_sched_barrier(0);
; #pragma unroll
;         for (int d = 0; d < 4; ++d) { const bf16x8 a = __builtin_shufflevector(vlo[ks & 1][d], vhi[ks & 1][d], 0, 1, 2, 3, 4, 5, 6, 7);
;             o[d] = __builtin_amdgcn_mfma_f32_32x32x16_bf16(a, pb[ks], o[d], 0, 0, 0); }
;         __builtin_amdgcn_sched_barrier(0);
;     }
; }
.Latt_smt_noresc:
	v_mov_b32_e32 v170, v169
	v_sub_f32_e32 v80, v80, v169
	v_sub_f32_e32 v81, v81, v169
	v_sub_f32_e32 v82, v82, v169
	v_sub_f32_e32 v83, v83, v169
	v_sub_f32_e32 v84, v84, v169
	v_sub_f32_e32 v85, v85, v169
	v_sub_f32_e32 v86, v86, v169
	v_sub_f32_e32 v87, v87, v169
	v_sub_f32_e32 v88, v88, v169
	v_sub_f32_e32 v89, v89, v169
	v_sub_f32_e32 v90, v90, v169
	v_sub_f32_e32 v91, v91, v169
	v_sub_f32_e32 v92, v92, v169
	v_sub_f32_e32 v93, v93, v169
	v_sub_f32_e32 v94, v94, v169
	v_sub_f32_e32 v95, v95, v169
	v_sub_f32_e32 v64, v64, v169
	v_sub_f32_e32 v65, v65, v169
	v_sub_f32_e32 v66, v66, v169
	v_sub_f32_e32 v67, v67, v169
	v_sub_f32_e32 v68, v68, v169
	v_sub_f32_e32 v69, v69, v169
	v_sub_f32_e32 v70, v70, v169
	v_sub_f32_e32 v71, v71, v169
	v_sub_f32_e32 v72, v72, v169
	v_sub_f32_e32 v73, v73, v169
	v_sub_f32_e32 v74, v74, v169
	v_sub_f32_e32 v75, v75, v169
	v_sub_f32_e32 v76, v76, v169
	v_sub_f32_e32 v77, v77, v169
	v_sub_f32_e32 v78, v78, v169
	v_sub_f32_e32 v79, v79, v169
	v_exp_f32_e32 v80, v80
	v_exp_f32_e32 v81, v81
	v_exp_f32_e32 v82, v82
	v_exp_f32_e32 v83, v83
	v_exp_f32_e32 v84, v84
	v_exp_f32_e32 v85, v85
	v_exp_f32_e32 v86, v86
	v_exp_f32_e32 v87, v87
	v_exp_f32_e32 v88, v88
	v_exp_f32_e32 v89, v89
	v_exp_f32_e32 v90, v90
	v_exp_f32_e32 v91, v91
	v_exp_f32_e32 v92, v92
	v_exp_f32_e32 v93, v93
	v_exp_f32_e32 v94, v94
	v_exp_f32_e32 v95, v95
	v_exp_f32_e32 v64, v64
	v_exp_f32_e32 v65, v65
	v_exp_f32_e32 v66, v66
	v_exp_f32_e32 v67, v67
	v_exp_f32_e32 v68, v68
	v_exp_f32_e32 v69, v69
	v_exp_f32_e32 v70, v70
	v_exp_f32_e32 v71, v71
	v_exp_f32_e32 v72, v72
	v_exp_f32_e32 v73, v73
	v_exp_f32_e32 v74, v74
	v_exp_f32_e32 v75, v75
	v_exp_f32_e32 v76, v76
	v_exp_f32_e32 v77, v77
	v_exp_f32_e32 v78, v78
	v_exp_f32_e32 v79, v79
	v_pk_add_f32 v[172:173], v[80:81], v[82:83]
	v_pk_add_f32 v[174:175], v[84:85], v[86:87]
	v_pk_add_f32 v[176:177], v[88:89], v[90:91]
	v_pk_add_f32 v[178:179], v[92:93], v[94:95]
	v_pk_add_f32 v[172:173], v[172:173], v[64:65]
	v_pk_add_f32 v[174:175], v[174:175], v[66:67]
	v_pk_add_f32 v[176:177], v[176:177], v[68:69]
	v_pk_add_f32 v[178:179], v[178:179], v[70:71]
	v_pk_add_f32 v[172:173], v[172:173], v[72:73]
	v_pk_add_f32 v[174:175], v[174:175], v[74:75]
	v_pk_add_f32 v[176:177], v[176:177], v[76:77]
	v_pk_add_f32 v[178:179], v[178:179], v[78:79]
	v_pk_add_f32 v[172:173], v[172:173], v[174:175]
	v_pk_add_f32 v[176:177], v[176:177], v[178:179]
	v_cvt_pk_bf16_f32 v71, v70, v71
	v_cvt_pk_bf16_f32 v70, v68, v69
	v_cvt_pk_bf16_f32 v69, v66, v67
	v_cvt_pk_bf16_f32 v68, v64, v65
	v_pk_add_f32 v[172:173], v[172:173], v[176:177]
	v_cvt_pk_bf16_f32 v64, v72, v73
	v_cvt_pk_bf16_f32 v65, v74, v75
	v_cvt_pk_bf16_f32 v66, v76, v77
	v_cvt_pk_bf16_f32 v67, v78, v79
	v_add_f32_e32 v170, v172, v173
	v_cvt_pk_bf16_f32 v72, v88, v89
	v_cvt_pk_bf16_f32 v73, v90, v91
	v_cvt_pk_bf16_f32 v74, v92, v93
	v_cvt_pk_bf16_f32 v75, v94, v95
	v_add_f32_e32 v168, v168, v170
	v_cvt_pk_bf16_f32 v76, v80, v81
	v_cvt_pk_bf16_f32 v77, v82, v83
	v_cvt_pk_bf16_f32 v78, v84, v85
	v_cvt_pk_bf16_f32 v79, v86, v87
	s_mul_i32 s4, s58, 0xb400
	v_add_u32_e32 v80, s77, v222
	v_add_u32_e32 v112, 0x6400, v80
	ds_read_b64_tr_b16 v[80:81], v112 offset:0
	ds_read_b64_tr_b16 v[82:83], v112 offset:2560
	ds_read_b64_tr_b16 v[84:85], v112 offset:64
	ds_read_b64_tr_b16 v[86:87], v112 offset:2624
	ds_read_b64_tr_b16 v[88:89], v112 offset:128
	ds_read_b64_tr_b16 v[90:91], v112 offset:2688
	ds_read_b64_tr_b16 v[92:93], v112 offset:192
	ds_read_b64_tr_b16 v[94:95], v112 offset:2752
	ds_read_b64_tr_b16 v[96:97], v112 offset:5120
	ds_read_b64_tr_b16 v[98:99], v112 offset:7680
	ds_read_b64_tr_b16 v[100:101], v112 offset:5184
	ds_read_b64_tr_b16 v[102:103], v112 offset:7744
	ds_read_b64_tr_b16 v[104:105], v112 offset:5248
	ds_read_b64_tr_b16 v[106:107], v112 offset:7808
	ds_read_b64_tr_b16 v[108:109], v112 offset:5312
	ds_read_b64_tr_b16 v[110:111], v112 offset:7872
	s_nop 0
	s_waitcnt lgkmcnt(8)
	s_waitcnt lgkmcnt(8)
	s_nop 0
	v_mfma_f32_32x32x16_bf16 v[48:63], v[80:83], v[76:79], v[48:63]
	v_mfma_f32_32x32x16_bf16 v[32:47], v[84:87], v[76:79], v[32:47]
	v_mfma_f32_32x32x16_bf16 v[16:31], v[88:91], v[76:79], v[16:31]
	v_mfma_f32_32x32x16_bf16 v[0:15], v[92:95], v[76:79], v[0:15]
	ds_read_b64_tr_b16 v[76:77], v112 offset:10240
	ds_read_b64_tr_b16 v[78:79], v112 offset:12800
	ds_read_b64_tr_b16 v[80:81], v112 offset:10304
	ds_read_b64_tr_b16 v[82:83], v112 offset:12864
	ds_read_b64_tr_b16 v[84:85], v112 offset:10368
	ds_read_b64_tr_b16 v[86:87], v112 offset:12928
	ds_read_b64_tr_b16 v[88:89], v112 offset:10432
	ds_read_b64_tr_b16 v[90:91], v112 offset:12992
	s_waitcnt lgkmcnt(8)
	s_waitcnt lgkmcnt(8)
	s_nop 0
	v_mfma_f32_32x32x16_bf16 v[48:63], v[96:99], v[72:75], v[48:63]
	v_mfma_f32_32x32x16_bf16 v[32:47], v[100:103], v[72:75], v[32:47]
	v_mfma_f32_32x32x16_bf16 v[16:31], v[104:107], v[72:75], v[16:31]
	v_mfma_f32_32x32x16_bf16 v[0:15], v[108:111], v[72:75], v[0:15]
	ds_read_b64_tr_b16 v[72:73], v112 offset:15360
	ds_read_b64_tr_b16 v[74:75], v112 offset:17920
	ds_read_b64_tr_b16 v[92:93], v112 offset:15424
	ds_read_b64_tr_b16 v[94:95], v112 offset:17984
	ds_read_b64_tr_b16 v[96:97], v112 offset:15488
	ds_read_b64_tr_b16 v[98:99], v112 offset:18048
	ds_read_b64_tr_b16 v[100:101], v112 offset:15552
	ds_read_b64_tr_b16 v[102:103], v112 offset:18112
	s_waitcnt lgkmcnt(8)
	s_waitcnt lgkmcnt(8)
	s_nop 0
	v_mfma_f32_32x32x16_bf16 v[48:63], v[76:79], v[68:71], v[48:63]
	v_mfma_f32_32x32x16_bf16 v[32:47], v[80:83], v[68:71], v[32:47]
	v_mfma_f32_32x32x16_bf16 v[16:31], v[84:87], v[68:71], v[16:31]
	v_mfma_f32_32x32x16_bf16 v[0:15], v[88:91], v[68:71], v[0:15]
	s_waitcnt lgkmcnt(0)
	s_waitcnt lgkmcnt(0)
	s_nop 0
	v_mfma_f32_32x32x16_bf16 v[48:63], v[72:75], v[64:67], v[48:63]
	v_mfma_f32_32x32x16_bf16 v[32:47], v[92:95], v[64:67], v[32:47]
	v_mfma_f32_32x32x16_bf16 v[16:31], v[96:99], v[64:67], v[16:31]
	v_mfma_f32_32x32x16_bf16 v[0:15], v[100:103], v[64:67], v[0:15]
	s_branch .LBB0_1007
